# hgrn_c: group-norm weights loaded once before the unit loop (VGPR+AGPR) instead of 4 loads per unit; operand loads spread over the VALU stretch
# speedup vs baseline: 1.0061x; 1.0061x over previous
; __device__ __forceinline__ void hgrn_c_load(Ctx& X, int u, RawC& R) {
;     const int hd = u & 7, c = u >> 3, t0 = c * 64, seg = X.tid >> 7, k = X.tid & 127;
;     const bf16_t* PR = (const bf16_t*)(X.ws + WS_PROJ);
;     const bf16_t* HQ = PR + 3 * TSZ; const bf16_t* HLF = PR + 4 * TSZ; const bf16_t* HV = PR + 5 * TSZ;
; #pragma unroll
;     for (int i = 0; i < 16; ++i) { const size_t off = (size_t)(t0 + 16 * seg + i) * 1024 + hd * 128 + k; R.lf[i] = HLF[off]; R.q[i] = HQ[off]; R.vv[i] = HV[off]; }
; __global__ void __launch_bounds__(512, 2) fwd_mega(Args a) {
;     ...
;     if (IN(5)) {
;         RawC cur; hgrn_c_load(X, blockIdx.x, cur);
.LBB0_727:
	s_cmp_lt_i32 s92, 6
	s_cselect_b64 s[2:3], -1, 0
	s_and_b64 s[12:13], s[2:3], s[0:1]
	s_andn2_b64 vcc, exec, s[12:13]
	s_cbranch_vccnz .LBB0_739
	v_readlane_b32 s0, v245, 0
	s_cmpk_gt_i32 s0, 0x7ff
	v_readlane_b32 s1, v245, 1
	s_cbranch_scc1 .LBB0_739
	s_add_u32 s14, s90, 0x11700000
	s_addc_u32 s15, s91, 0
	s_add_u32 s16, s90, 0x13700000
	s_addc_u32 s17, s91, 0
	s_add_u32 s18, s90, 0x15700000
	v_lshrrev_b32_e32 v70, 3, v209
	s_addc_u32 s19, s91, 0
	v_and_b32_e32 v71, 0x70, v70
	s_and_b32 s0, s54, 0xffffffc0
	v_readlane_b32 s34, v245, 0
	v_add_u32_e32 v0, s0, v71
	s_lshl_b32 s36, s34, 7
	v_and_b32_e32 v59, 0x7f, v209
	v_or_b32_e32 v2, 8, v0
	s_and_b32 s0, s36, 0x380
	v_or_b32_e32 v22, 13, v0
	v_or_b32_e32 v26, 14, v0
	v_ashrrev_i32_e32 v3, 31, v2
	v_or_b32_e32 v1, s0, v59
	v_or_b32_e32 v6, 9, v0
	v_or_b32_e32 v10, 10, v0
	v_or_b32_e32 v12, 11, v0
	v_or_b32_e32 v14, 12, v0
	v_ashrrev_i32_e32 v23, 31, v22
	v_ashrrev_i32_e32 v27, 31, v26
	v_or_b32_e32 v30, 15, v0
	v_lshlrev_b64 v[2:3], 11, v[2:3]
	v_lshlrev_b32_e32 v38, 1, v1
	v_ashrrev_i32_e32 v7, 31, v6
	v_ashrrev_i32_e32 v11, 31, v10
	v_ashrrev_i32_e32 v13, 31, v12
	v_ashrrev_i32_e32 v15, 31, v14
	v_lshlrev_b64 v[22:23], 11, v[22:23]
	v_lshlrev_b64 v[26:27], 11, v[26:27]
	v_ashrrev_i32_e32 v31, 31, v30
	v_or_b32_e32 v2, v2, v38
	v_lshlrev_b64 v[6:7], 11, v[6:7]
	v_lshlrev_b64 v[16:17], 11, v[10:11]
	v_lshlrev_b64 v[18:19], 11, v[12:13]
	v_lshlrev_b64 v[14:15], 11, v[14:15]
	v_or_b32_e32 v22, v22, v38
	v_or_b32_e32 v26, v26, v38
	v_lshlrev_b64 v[30:31], 11, v[30:31]
	v_lshl_add_u64 v[4:5], s[18:19], 0, v[2:3]
	v_or_b32_e32 v6, v6, v38
	v_or_b32_e32 v16, v16, v38
	v_or_b32_e32 v18, v18, v38
	v_or_b32_e32 v14, v14, v38
	v_lshl_add_u64 v[24:25], s[18:19], 0, v[22:23]
	v_lshl_add_u64 v[28:29], s[18:19], 0, v[26:27]
	v_or_b32_e32 v30, v30, v38
	v_lshl_add_u64 v[8:9], s[18:19], 0, v[6:7]
	v_lshl_add_u64 v[10:11], s[18:19], 0, v[16:17]
	v_lshl_add_u64 v[12:13], s[18:19], 0, v[18:19]
	v_lshl_add_u64 v[20:21], s[18:19], 0, v[14:15]
	v_lshl_add_u64 v[32:33], s[18:19], 0, v[30:31]
	global_load_ushort v40, v[4:5], off
	global_load_ushort v41, v[8:9], off
	global_load_ushort v42, v[10:11], off
	global_load_ushort v43, v[12:13], off
	global_load_ushort v44, v[20:21], off
	global_load_ushort v45, v[24:25], off
	global_load_ushort v46, v[28:29], off
	global_load_ushort v47, v[32:33], off
	v_lshl_add_u64 v[4:5], s[14:15], 0, v[30:31]
	v_lshl_add_u64 v[24:25], s[14:15], 0, v[26:27]
	v_lshl_add_u64 v[28:29], s[14:15], 0, v[22:23]
	v_lshl_add_u64 v[22:23], s[16:17], 0, v[22:23]
	v_lshl_add_u64 v[20:21], s[16:17], 0, v[30:31]
	v_lshl_add_u64 v[26:27], s[16:17], 0, v[26:27]
	v_lshl_add_u64 v[30:31], s[14:15], 0, v[14:15]
	v_lshl_add_u64 v[32:33], s[16:17], 0, v[14:15]
	global_load_ushort v12, v[4:5], off
	global_load_ushort v8, v[20:21], off
	global_load_ushort v13, v[24:25], off
	global_load_ushort v9, v[26:27], off
	global_load_ushort v14, v[28:29], off
	global_load_ushort v10, v[22:23], off
	global_load_ushort v15, v[30:31], off
	global_load_ushort v11, v[32:33], off
	v_lshl_add_u64 v[4:5], s[14:15], 0, v[18:19]
	v_lshl_add_u64 v[18:19], s[16:17], 0, v[18:19]
	v_lshl_add_u64 v[22:23], s[14:15], 0, v[6:7]
	v_lshl_add_u64 v[6:7], s[16:17], 0, v[6:7]
	v_lshl_add_u64 v[24:25], s[14:15], 0, v[2:3]
	v_lshl_add_u64 v[2:3], s[16:17], 0, v[2:3]
	v_ashrrev_i32_e32 v1, 31, v0
	v_lshl_add_u64 v[20:21], s[14:15], 0, v[16:17]
	v_lshl_add_u64 v[16:17], s[16:17], 0, v[16:17]
	global_load_ushort v121, v[4:5], off
	global_load_ushort v152, v[18:19], off
	global_load_ushort v115, v[20:21], off
	global_load_ushort v154, v[16:17], off
	global_load_ushort v119, v[22:23], off
	global_load_ushort v155, v[6:7], off
	global_load_ushort v132, v[24:25], off
	global_load_ushort v156, v[2:3], off
	v_lshlrev_b64 v[2:3], 11, v[0:1]
	v_or_b32_e32 v6, 1, v0
	v_or_b32_e32 v18, 2, v0
	v_or_b32_e32 v22, 3, v0
	v_or_b32_e32 v26, 4, v0
	v_or_b32_e32 v30, 5, v0
	v_or_b32_e32 v34, 6, v0
	v_or_b32_e32 v0, 7, v0
	v_ashrrev_i32_e32 v7, 31, v6
	v_ashrrev_i32_e32 v19, 31, v18
	v_ashrrev_i32_e32 v23, 31, v22
	v_ashrrev_i32_e32 v27, 31, v26
	v_ashrrev_i32_e32 v31, 31, v30
	v_ashrrev_i32_e32 v35, 31, v34
	v_ashrrev_i32_e32 v1, 31, v0
	v_or_b32_e32 v2, v2, v38
	v_lshlrev_b64 v[6:7], 11, v[6:7]
	v_lshlrev_b64 v[18:19], 11, v[18:19]
	v_lshlrev_b64 v[22:23], 11, v[22:23]
	v_lshlrev_b64 v[26:27], 11, v[26:27]
	v_lshlrev_b64 v[30:31], 11, v[30:31]
	v_lshlrev_b64 v[34:35], 11, v[34:35]
	v_lshlrev_b64 v[0:1], 11, v[0:1]
	v_lshl_add_u64 v[4:5], s[18:19], 0, v[2:3]
	v_or_b32_e32 v6, v6, v38
	v_or_b32_e32 v18, v18, v38
	v_or_b32_e32 v22, v22, v38
	v_or_b32_e32 v26, v26, v38
	v_or_b32_e32 v30, v30, v38
	v_or_b32_e32 v34, v34, v38
	v_or_b32_e32 v0, v0, v38
	v_lshl_add_u64 v[16:17], s[18:19], 0, v[6:7]
	v_lshl_add_u64 v[20:21], s[18:19], 0, v[18:19]
	v_lshl_add_u64 v[24:25], s[18:19], 0, v[22:23]
	v_lshl_add_u64 v[28:29], s[18:19], 0, v[26:27]
	v_lshl_add_u64 v[32:33], s[18:19], 0, v[30:31]
	v_lshl_add_u64 v[36:37], s[18:19], 0, v[34:35]
	v_lshl_add_u64 v[38:39], s[18:19], 0, v[0:1]
	global_load_ushort v48, v[4:5], off
	global_load_ushort v49, v[16:17], off
	global_load_ushort v50, v[20:21], off
	global_load_ushort v51, v[24:25], off
	global_load_ushort v52, v[28:29], off
	global_load_ushort v53, v[32:33], off
	global_load_ushort v54, v[36:37], off
	global_load_ushort v55, v[38:39], off
	v_lshl_add_u64 v[4:5], s[14:15], 0, v[0:1]
	v_lshl_add_u64 v[0:1], s[16:17], 0, v[0:1]
	v_lshl_add_u64 v[16:17], s[14:15], 0, v[34:35]
	v_lshl_add_u64 v[20:21], s[16:17], 0, v[34:35]
	v_lshl_add_u64 v[24:25], s[14:15], 0, v[30:31]
	v_lshl_add_u64 v[28:29], s[16:17], 0, v[30:31]
; #define LAS __attribute__((address_space(3)))
; __device__ __forceinline__ void hgrn_c_load(Ctx& X, int u, RawC& R) {
;     const int hd = u & 7, c = u >> 3, t0 = c * 64, seg = X.tid >> 7, k = X.tid & 127;
;     const bf16_t* PR = (const bf16_t*)(X.ws + WS_PROJ);
;     const bf16_t* HQ = PR + 3 * TSZ; const bf16_t* HLF = PR + 4 * TSZ; const bf16_t* HV = PR + 5 * TSZ;
; #pragma unroll
;     for (int i = 0; i < 16; ++i) { const size_t off = (size_t)(t0 + 16 * seg + i) * 1024 + hd * 128 + k; R.lf[i] = HLF[off]; R.q[i] = HQ[off]; R.vv[i] = HV[off]; }
; }
; __device__ __forceinline__ void hgrn_c_compute(Ctx& X, int u, const RawC& R) {
;     const int hd = u & 7, c = u >> 3, t0 = c * 64;
;     const int tid = X.tid, seg = tid >> 7, k = tid & 127, lane = X.lane, w = X.wave, r = lane & 31, h = lane >> 5;
;     LAS bf16_t* QH = (LAS bf16_t*)(X.lds);
;     LAS bf16_t* QT = (LAS bf16_t*)(X.lds + 17408);
;     LAS bf16_t* KT2 = (LAS bf16_t*)(X.lds + 34816);
;     LAS bf16_t* VT = (LAS bf16_t*)(X.lds + 52224);
;     LAS bf16_t* AM = (LAS bf16_t*)(X.lds + 70656);
;     LAS float* OF = (LAS float*)(X.lds + 79872);
;     LAS float* SEG = (LAS float*)(X.lds + 113664);
;     const bf16_t* HG = (const bf16_t*)(X.ws + WS_PROJ) + 6 * TSZ;
;     const int tt2 = w & 1, vt2 = w >> 1;
;     bf16x8 sfr[8];
;     {
;         const bf16_t* sb = (const bf16_t*)(X.ws + WS_SBUF) + (size_t)u * 16384 + (32 * vt2 + r) * 128 + 8 * h;
; #pragma unroll
;         for (int kk = 0; kk < 8; ++kk) sfr[kk] = *(const bf16x8*)(sb + 16 * kk);
;     }
;     const int tn = tid >> 3, sub = tid & 7;
;     const u32x4 g0 = *(const u32x4*)(HG + (size_t)(t0 + tn) * 1024 + hd * 128 + 16 * sub), g1 = *(const u32x4*)(HG + (size_t)(t0 + tn) * 1024 + hd * 128 + 16 * sub + 8);
;     ...
;             const float w0 = X.gnorm_w[16 * sub + 2 * e], w1 = X.gnorm_w[16 * sub + 2 * e + 1];
	v_lshl_add_u64 v[30:31], s[14:15], 0, v[26:27]
	v_lshl_add_u64 v[26:27], s[16:17], 0, v[26:27]
	global_load_ushort v149, v[4:5], off
	global_load_ushort v162, v[0:1], off
	global_load_ushort v150, v[16:17], off
	global_load_ushort v163, v[20:21], off
	global_load_ushort v151, v[24:25], off
	global_load_ushort v160, v[28:29], off
	global_load_ushort v153, v[30:31], off
	global_load_ushort v161, v[26:27], off
	v_lshl_add_u64 v[0:1], s[14:15], 0, v[22:23]
	v_lshl_add_u64 v[4:5], s[16:17], 0, v[22:23]
	v_lshl_add_u64 v[16:17], s[14:15], 0, v[18:19]
	v_lshl_add_u64 v[18:19], s[16:17], 0, v[18:19]
	v_lshl_add_u64 v[20:21], s[14:15], 0, v[6:7]
	v_lshl_add_u64 v[6:7], s[16:17], 0, v[6:7]
	v_lshl_add_u64 v[22:23], s[14:15], 0, v[2:3]
	v_lshl_add_u64 v[2:3], s[16:17], 0, v[2:3]
	global_load_ushort v157, v[0:1], off
	global_load_ushort v165, v[4:5], off
	global_load_ushort v158, v[16:17], off
	global_load_ushort v166, v[18:19], off
	global_load_ushort v159, v[20:21], off
	global_load_ushort v167, v[6:7], off
	global_load_ushort v164, v[22:23], off
	global_load_ushort v168, v[2:3], off
	s_add_u32 s20, s90, 0x17700000
	v_readlane_b32 s30, v245, 21
	s_addc_u32 s21, s91, 0
	s_lshr_b32 s22, s30, 7
	s_movk_i32 s2, 0xff
	s_lshl_b32 s28, s22, 5
	s_add_i32 s0, 0, 0x1bc00
	v_cmp_lt_u32_e64 s[4:5], s2, v209
	s_movk_i32 s2, 0x17f
	v_cmp_lt_u32_e64 s[6:7], s2, v209
	s_movk_i32 s2, 0x1ff
	s_cmpk_lt_u32 s30, 0x100
	v_cmp_lt_u32_e64 s[8:9], s2, v209
	s_cselect_b64 s[24:25], -1, 0
	s_lshr_b32 s2, s30, 1
	s_and_b32 s37, s2, 32
	s_cmp_lg_u32 s22, 1
	v_lshrrev_b32_e32 v0, 7, v209
	v_lshrrev_b32_e32 v1, 5, v208
	v_lshlrev_b32_e32 v3, 4, v209
	s_cselect_b64 s[2:3], -1, 0
	s_bitcmp1_b32 s30, 6
	v_and_b32_e32 v72, 31, v209
	v_and_b32_e32 v16, 0x70, v3
	v_mul_u32_u24_e32 v3, 0x880, v0
	v_lshlrev_b32_e32 v20, 5, v0
	s_cselect_b64 s[10:11], -1, 0
	v_lshlrev_b32_e32 v0, 4, v1
	v_or_b32_e32 v2, s28, v72
	s_or_b64 s[26:27], s[2:3], s[10:11]
	v_add_u32_e32 v58, 0, v0
	s_movk_i32 s10, 0x110
	v_mad_u64_u32 v[60:61], s[2:3], v2, s10, v[58:59]
	s_add_i32 s2, 0, 0x11400
	s_lshl_b32 s3, s22, 6
	s_movk_i32 s29, 0x90
	s_add_i32 s3, s2, s3
	v_lshl_add_u32 v81, v1, 3, s3
	v_add_u32_e32 v96, s2, v0
	v_mad_u64_u32 v[62:63], s[2:3], v2, s29, v[58:59]
	s_add_i32 s3, 0, 0x13800
	v_mul_u32_u24_e32 v0, 0x210, v70
	v_lshlrev_b32_e32 v56, 2, v16
	v_add3_u32 v97, s3, v0, v56
	v_mbcnt_lo_u32_b32 v0, -1, 0
	v_mbcnt_hi_u32_b32 v0, -1, v0
	v_and_b32_e32 v2, 64, v0
	v_lshlrev_b32_e32 v78, 2, v1
	v_xor_b32_e32 v1, 1, v0
	v_add_u32_e32 v2, 64, v2
	v_readlane_b32 s35, v245, 1
	s_and_b32 s2, s30, 0xffffff80
	v_cmp_lt_i32_e32 vcc, v1, v2
	s_add_i32 s2, s3, s2
	v_readlane_b32 s56, v245, 5
	v_cndmask_b32_e32 v1, v0, v1, vcc
	s_ashr_i32 s35, s34, 31
	v_and_b32_e32 v18, 32, v209
	v_mov_b32_e32 v57, 0
	v_lshl_add_u32 v63, v72, 2, s2
	v_lshlrev_b32_e32 v98, 2, v1
	v_xor_b32_e32 v1, 2, v0
	v_readlane_b32 s57, v245, 6
	s_lshl_b64 s[2:3], s[34:35], 15
	v_lshrrev_b32_e32 v18, 1, v18
	v_lshlrev_b32_e32 v21, 7, v72
	v_cmp_lt_i32_e32 vcc, v1, v2
	v_lshl_add_u64 v[64:65], s[56:57], 0, v[56:57]
	global_load_dwordx4 v[236:239], v[64:65], off offset:16
	global_load_dwordx4 v[240:243], v[64:65], off
	global_load_dwordx4 a[0:3], v[64:65], off offset:48
	global_load_dwordx4 a[4:7], v[64:65], off offset:32
	v_or_b32_e32 v18, s2, v18
	v_mov_b32_e32 v19, s3
	v_lshl_or_b32 v56, s22, 12, v21
	v_cndmask_b32_e32 v1, v0, v1, vcc
	v_lshl_add_u64 v[18:19], v[56:57], 1, v[18:19]
	v_lshlrev_b32_e32 v99, 2, v1
	v_xor_b32_e32 v1, 4, v0
	v_lshl_add_u64 v[18:19], s[90:91], 0, v[18:19]
	s_mov_b64 s[2:3], 0xb700080
	v_cmp_lt_i32_e32 vcc, v1, v2
	v_lshl_add_u64 v[66:67], v[18:19], 0, s[2:3]
	s_ashr_i32 s3, s94, 31
	s_mov_b32 s2, s94
	v_lshl_add_u32 v73, v209, 2, s0
	v_lshl_add_u32 v74, v59, 2, s0
	s_movk_i32 s0, 0x80
	v_or_b32_e32 v3, v3, v59
	v_mad_u32_u24 v17, v59, s29, 0
	v_or_b32_e32 v76, s37, v72
	v_or_b32_e32 v80, s28, v78
	v_cndmask_b32_e32 v0, v0, v1, vcc
	s_mov_b32 s39, 0x5040100
	s_lshl_b64 s[28:29], s[2:3], 15
	s_mov_b32 s3, 0x800000
	s_mov_b32 s2, s34
	s_mov_b32 s23, 0
	v_cmp_gt_u32_e64 s[0:1], s0, v209
	v_lshl_add_u32 v75, v3, 1, 0
	v_mul_u32_u24_e32 v77, 0x90, v76
	v_mul_u32_u24_e32 v61, 0x110, v76
	v_mad_u32_u24 v79, v76, s10, v58
	v_or_b32_e32 v82, 2, v80
	v_or_b32_e32 v83, 3, v80
	v_or_b32_e32 v84, 8, v80
	v_or_b32_e32 v85, 9, v80
	v_or_b32_e32 v86, 10, v80
	v_or_b32_e32 v87, 11, v80
	v_or_b32_e32 v88, 16, v80
	v_or_b32_e32 v89, 17, v80
	v_or_b32_e32 v90, 18, v80
	v_or_b32_e32 v91, 19, v80
	v_or_b32_e32 v92, 24, v80
	v_or_b32_e32 v93, 25, v80
	v_or_b32_e32 v94, 26, v80
	v_or_b32_e32 v95, 27, v80
	s_movk_i32 s38, 0x210
	v_lshlrev_b32_e32 v100, 2, v0
	v_readlane_b32 s58, v245, 7
	v_readlane_b32 s59, v245, 8
	v_readlane_b32 s60, v245, 9
	v_readlane_b32 s61, v245, 10
	v_readlane_b32 s62, v245, 11
	v_readlane_b32 s63, v245, 12
	v_readlane_b32 s64, v245, 13
	v_readlane_b32 s65, v245, 14
	v_readlane_b32 s66, v245, 15
	v_readlane_b32 s67, v245, 16
	v_readlane_b32 s68, v245, 17
	v_readlane_b32 s69, v245, 18
	v_readlane_b32 s70, v245, 19
	v_readlane_b32 s71, v245, 20
	v_mul_u32_u24_e32 v101, 0x90, v72
	v_mul_u32_u24_e32 v102, 0x110, v72
	s_waitcnt vmcnt(22)
; __device__ __forceinline__ void hgrn_c_compute(Ctx& X, int u, const RawC& R) {
;     ...
;         for (int i = 0; i < 8; ++i) pv[i] = (unsigned)R.vv[2 * i] | ((unsigned)R.vv[2 * i + 1] << 16);
	v_perm_b32 v0, v49, v48, s39
	s_waitcnt vmcnt(20)
	v_perm_b32 v1, v51, v50, s39
	s_waitcnt vmcnt(18)
	v_perm_b32 v2, v53, v52, s39
	s_waitcnt vmcnt(16)
	v_perm_b32 v3, v55, v54, s39
	v_perm_b32 v4, v41, v40, s39
	v_perm_b32 v5, v43, v42, s39
	v_perm_b32 v6, v45, v44, s39
	v_perm_b32 v7, v47, v46, s39
	s_lshl_b32 s40, s94, 7
	v_lshlrev_b32_e32 v56, 1, v16
	v_add_u32_e32 v103, v17, v20
	v_mov_b32_e32 v104, 0x358637bd
	s_mov_b64 s[30:31], 0x7700800
	s_mov_b32 s41, 0x7700000
	v_writelane_b32 v245, s2, 0
	s_mov_b32 s42, s34
	s_nop 0
	v_writelane_b32 v245, s3, 1
	s_waitcnt vmcnt(0)
	v_lshrrev_b32_e32 v203, 6, v209
	v_and_b32_e32 v206, 63, v209
	v_lshrrev_b32_e32 v207, 4, v206
	v_and_b32_e32 v204, 15, v206
	v_xor_b32_e32 v204, v204, v207
	v_lshlrev_b32_e32 v204, 4, v204
	v_lshl_add_u32 v204, v207, 8, v204
	v_lshl_add_u32 v204, v203, 12, v204
	v_readfirstlane_b32 s72, v203
	v_lshrrev_b32_e32 v205, 1, v203
	v_and_b32_e32 v207, 31, v206
	v_lshl_add_u32 v207, v205, 5, v207
	v_lshlrev_b32_e32 v207, 8, v207
	v_lshrrev_b32_e32 v206, 5, v206
	v_lshl_add_u32 v207, v206, 4, v207
	v_add_u32_e32 v207, 0x80, v207
	s_lshl_b32 s72, s72, 12
	s_add_i32 s72, s72, 0x1c800
	v_mov_b32_e32 v194, v204
	v_sub_u32_e32 v194, v194, v207
	v_ashrrev_i32_e32 v195, 31, v194
	v_xor_b32_e32 v196, 0x40, v204
	v_add_u32_e32 v196, 0x400, v196
	v_sub_u32_e32 v196, v196, v207
	v_ashrrev_i32_e32 v197, 31, v196
	v_xor_b32_e32 v198, 0x80, v204
	v_add_u32_e32 v198, 0x800, v198
	v_sub_u32_e32 v198, v198, v207
	v_ashrrev_i32_e32 v199, 31, v198
	v_xor_b32_e32 v200, 0xc0, v204
	v_add_u32_e32 v200, 0xc00, v200
	v_sub_u32_e32 v200, v200, v207
	v_ashrrev_i32_e32 v201, 31, v200
	v_and_b32_e32 v202, 63, v209
	v_and_b32_e32 v204, 15, v202
	v_xor_b32_e32 v204, v204, v206
	v_and_b32_e32 v202, 31, v202
	v_lshlrev_b32_e32 v202, 8, v202
	v_lshl_add_u32 v202, v204, 4, v202
	v_lshl_add_u32 v202, v205, 13, v202
	v_add_u32_e32 v202, 0x1c800, v202
	s_branch .LBB0_733

; #define LAS __attribute__((address_space(3)))
; __device__ __forceinline__ int crow(int reg, int h) { return (reg & 3) + 8 * (reg >> 2) + 4 * h; }
; #define MFMA32(a, b, c) __builtin_amdgcn_mfma_f32_32x32x16_bf16((a), (b), (c), 0, 0, 0)
; __device__ __forceinline__ void hgrn_c_compute(Ctx& X, int u, const RawC& R) {
;     ...
;     {
;         f32x16 acc;
; #pragma unroll
;         for (int i = 0; i < 16; ++i) acc[i] = 0.f;
; #pragma unroll
;         for (int kk = 0; kk < 8; ++kk) {
;             const bf16x8 af = *(const LAS bf16x8*)(QH + (32 * tt2 + r) * 136 + 16 * kk + 8 * h);
;             acc = MFMA32(af, sfr[kk], acc);
;         }
; #pragma unroll
;         for (int ks = 0; ks < 4; ++ks) {
;             const bf16x8 af = *(const LAS bf16x8*)(AM + (32 * tt2 + r) * 72 + 16 * ks + 8 * h);
;             const bf16x8 bfr = *(const LAS bf16x8*)(VT + (32 * vt2 + r) * 72 + 16 * ks + 8 * h);
;             acc = MFMA32(af, bfr, acc);
;         }
; #pragma unroll
;         for (int i = 0; i < 16; ++i) OF[(32 * tt2 + crow(i, h)) * 132 + 32 * vt2 + r] = acc[i];
;     }
;     __syncthreads();
.LBB0_732:
	v_add_u32_e32 v119, v58, v119
	s_waitcnt vmcnt(0) lgkmcnt(0)
	s_barrier
	ds_read_b128 v[52:55], v202
	v_xor_b32_e32 v203, 0x20, v202
	ds_read_b128 v[48:51], v203
	v_xor_b32_e32 v203, 0x40, v202
	ds_read_b128 v[44:47], v203
	v_xor_b32_e32 v203, 0x60, v202
	ds_read_b128 v[40:43], v203
	v_xor_b32_e32 v203, 0x80, v202
	ds_read_b128 v[36:39], v203
	v_xor_b32_e32 v203, 0xa0, v202
	ds_read_b128 v[32:35], v203
	v_xor_b32_e32 v203, 0xc0, v202
	ds_read_b128 v[24:27], v203
	v_xor_b32_e32 v203, 0xe0, v202
	ds_read_b128 v[20:23], v203
	ds_read_b128 v[0:3], v119
	ds_read_b128 v[150:153], v119 offset:32
	s_waitcnt lgkmcnt(1)
	v_mfma_f32_32x32x16_bf16 v[0:15], v[0:3], v[52:55], 0
	v_add_u32_e32 v115, v96, v115
	s_waitcnt vmcnt(1)
	v_lshlrev_b32_e32 v174, 16, v16
	v_and_b32_e32 v175, 0xffff0000, v16
	v_lshlrev_b32_e32 v176, 16, v19
	v_and_b32_e32 v177, 0xffff0000, v19
	v_add_u32_e32 v121, s2, v78
	s_waitcnt vmcnt(0)
	v_lshlrev_b32_e32 v170, 16, v28
	s_waitcnt lgkmcnt(0)
	v_mfma_f32_32x32x16_bf16 v[0:15], v[150:153], v[48:51], v[0:15]
	ds_read_b128 v[48:51], v119 offset:64
	ds_read_b128 v[52:55], v119 offset:96
	v_and_b32_e32 v171, 0xffff0000, v28
	v_lshlrev_b32_e32 v172, 16, v29
	v_and_b32_e32 v173, 0xffff0000, v29
	s_add_i32 s54, s54, s50
	s_add_i32 s36, s36, s40
	v_lshl_add_u64 v[66:67], v[66:67], 0, s[28:29]
	s_waitcnt lgkmcnt(1)
	v_mfma_f32_32x32x16_bf16 v[0:15], v[48:51], v[44:47], v[0:15]
	v_mov_b32_e32 v168, v114
	v_mov_b32_e32 v167, v112
	v_mov_b32_e32 v166, v113
	v_mov_b32_e32 v165, v122
	v_mov_b32_e32 v161, v123
	v_mov_b32_e32 v160, v124
	v_mov_b32_e32 v163, v128
	s_waitcnt lgkmcnt(0)
	v_mfma_f32_32x32x16_bf16 v[0:15], v[52:55], v[40:43], v[0:15]
	ds_read_b128 v[40:43], v119 offset:128
	ds_read_b128 v[44:47], v119 offset:160
	v_mov_b32_e32 v162, v129
	v_mov_b32_e32 v156, v137
	v_mov_b32_e32 v155, v138
	v_mov_b32_e32 v154, v139
	v_mov_b32_e32 v152, v148
	v_mov_b32_e32 v164, v105
	s_waitcnt lgkmcnt(1)
	v_mfma_f32_32x32x16_bf16 v[0:15], v[40:43], v[36:39], v[0:15]
	ds_read_b128 v[36:39], v62 offset:52224
	ds_read_b128 v[40:43], v62 offset:52256
	ds_read_b128 v[48:51], v119 offset:192
	v_mov_b32_e32 v159, v106
	v_mov_b32_e32 v158, v107
	v_mov_b32_e32 v157, v108
	v_mov_b32_e32 v153, v109
	v_mov_b32_e32 v151, v116
	v_mov_b32_e32 v150, v110
	s_waitcnt lgkmcnt(3)
	v_mfma_f32_32x32x16_bf16 v[0:15], v[44:47], v[32:35], v[0:15]
	ds_read_b128 v[32:35], v62 offset:52288
	ds_read_b128 v[44:47], v62 offset:52320
	ds_read_b128 v[52:55], v119 offset:224
	v_mov_b32_e32 v149, v111
	v_mov_b32_e32 v132, v118
	v_mov_b32_e32 v119, v120
	s_waitcnt lgkmcnt(3)
	v_mfma_f32_32x32x16_bf16 v[0:15], v[48:51], v[24:27], v[0:15]
	ds_read_b128 v[24:27], v115
	v_lshlrev_b32_e32 v48, 16, v30
	v_and_b32_e32 v49, 0xffff0000, v30
	v_lshlrev_b32_e32 v50, 16, v31
	v_and_b32_e32 v51, 0xffff0000, v31
	s_waitcnt lgkmcnt(1)
	v_mfma_f32_32x32x16_bf16 v[0:15], v[52:55], v[20:23], v[0:15]
	v_lshlrev_b32_e32 v52, 16, v17
	v_and_b32_e32 v53, 0xffff0000, v17
	v_lshlrev_b32_e32 v54, 16, v18
	v_and_b32_e32 v55, 0xffff0000, v18
	ds_read_b128 v[16:19], v115 offset:32
	ds_read_b128 v[20:23], v115 offset:64
	s_waitcnt lgkmcnt(2)
	v_mfma_f32_32x32x16_bf16 v[0:15], v[24:27], v[36:39], v[0:15]
	v_mad_i32_i24 v24, v121, s38, v63
	v_add_u32_e32 v25, 0x2400, v24
	v_add_u32_e32 v26, 0x3000, v24
	v_add_u32_e32 v27, 0x3400, v24
	v_lshlrev_b64 v[36:37], 12, v[68:69]
	v_lshl_add_u64 v[36:37], s[90:91], 0, v[36:37]
	v_lshl_add_u64 v[36:37], v[36:37], 0, s[22:23]
	s_waitcnt lgkmcnt(1)
	v_mfma_f32_32x32x16_bf16 v[0:15], v[16:19], v[40:43], v[0:15]
	ds_read_b128 v[16:19], v115 offset:96
	v_lshl_add_u64 v[36:37], v[36:37], 0, v[56:57]
	v_mov_b32_e32 v115, v117
	v_mov_b32_e32 v121, v131
	s_waitcnt lgkmcnt(1)
	v_mfma_f32_32x32x16_bf16 v[0:15], v[20:23], v[32:35], v[0:15]
	v_add_u32_e32 v20, 0x400, v24
	v_add_u32_e32 v21, 0x1000, v24
	v_add_u32_e32 v22, 0x1400, v24
	v_add_u32_e32 v23, 0x2000, v24
	s_waitcnt lgkmcnt(0)
	v_mfma_f32_32x32x16_bf16 v[0:15], v[16:19], v[44:47], v[0:15]
	s_nop 11
	ds_write2_b32 v24, v0, v1 offset1:132
	ds_write2_b32 v20, v2, v3 offset0:8 offset1:140
	ds_write2_b32 v21, v4, v5 offset0:32 offset1:164
	ds_write2_b32 v22, v6, v7 offset0:40 offset1:172
	ds_write2_b32 v23, v8, v9 offset0:64 offset1:196
	ds_write2_b32 v25, v10, v11 offset0:72 offset1:204
	ds_write2_b32 v26, v12, v13 offset0:96 offset1:228
	ds_write2_b32 v27, v14, v15 offset0:104 offset1:236
	s_waitcnt lgkmcnt(0)
	s_barrier
; #define LAS __attribute__((address_space(3)))
; __device__ __forceinline__ unsigned pk2_rne(float lo, float hi) { const f32x2_t f = {lo, hi}; return __builtin_bit_cast(unsigned, __builtin_convertvector(f, bf16x2_t)); }
; __device__ __forceinline__ float bflo(unsigned w) { return __uint_as_float(w << 16); }
; __device__ __forceinline__ float bfhi(unsigned w) { return __uint_as_float(w & 0xffff0000u); }
; __device__ __forceinline__ void hgrn_c_compute(Ctx& X, int u, const RawC& R) {
;     ...
;     {
;         float ov[16]; float ss = 0.f;
; #pragma unroll
;         for (int e = 0; e < 4; ++e) { const f32x4 q4 = *(const LAS f32x4*)(OF + tn * 132 + 16 * sub + 4 * e); ov[4 * e] = q4[0]; ov[4 * e + 1] = q4[1]; ov[4 * e + 2] = q4[2]; ov[4 * e + 3] = q4[3]; }
; #pragma unroll
;         for (int e = 0; e < 16; ++e) ss += ov[e] * ov[e];
;         ss += __shfl_xor(ss, 1); ss += __shfl_xor(ss, 2); ss += __shfl_xor(ss, 4);
;         const float rinv = rsqrtf(ss * (1.f / 128.f) + EPS);
;         const unsigned gw[8] = {g0.x, g0.y, g0.z, g0.w, g1.x, g1.y, g1.z, g1.w};
;         unsigned pw[8];
; #pragma unroll
;         for (int e = 0; e < 8; ++e) {
;             const float w0 = X.gnorm_w[16 * sub + 2 * e], w1 = X.gnorm_w[16 * sub + 2 * e + 1];
;             pw[e] = pk2_rne(ov[2 * e] * rinv * w0 * bflo(gw[e]), ov[2 * e + 1] * rinv * w1 * bfhi(gw[e]));
;         }
;         bf16_t* yp = (bf16_t*)(X.ws + WS_H) + (size_t)(t0 + tn) * D + 1024 + hd * 128 + 16 * sub;
;         *(u32x4*)(yp) = (u32x4){pw[0], pw[1], pw[2], pw[3]}; *(u32x4*)(yp + 8) = (u32x4){pw[4], pw[5], pw[6], pw[7]};
;     }
	ds_read_b128 v[20:23], v97
	ds_read_b128 v[24:27], v97 offset:32
	ds_read_b128 v[28:31], v97 offset:48
	ds_read_b128 v[32:35], v97 offset:16
	v_mov_b32_e32 v11, v147
	v_mov_b32_e32 v10, v146
	s_waitcnt lgkmcnt(3)
	v_mul_f32_e32 v46, v21, v21
	v_fmac_f32_e32 v46, v20, v20
	v_fmac_f32_e32 v46, v22, v22
	v_fmac_f32_e32 v46, v23, v23
	s_waitcnt lgkmcnt(0)
	v_fmac_f32_e32 v46, v32, v32
	v_fmac_f32_e32 v46, v33, v33
	v_fmac_f32_e32 v46, v34, v34
	v_pk_mul_f32 v[40:41], v[24:25], v[24:25]
	v_fmac_f32_e32 v46, v35, v35
	v_add_f32_e32 v40, v40, v46
	v_pk_mul_f32 v[38:39], v[26:27], v[26:27]
	v_add_f32_e32 v40, v41, v40
	v_add_f32_e32 v38, v38, v40
	v_pk_mul_f32 v[44:45], v[28:29], v[28:29]
	v_add_f32_e32 v38, v39, v38
	v_add_f32_e32 v38, v44, v38
	v_pk_mul_f32 v[42:43], v[30:31], v[30:31]
	v_add_f32_e32 v38, v45, v38
	v_add_f32_e32 v38, v42, v38
	v_add_f32_e32 v38, v43, v38
	ds_bpermute_b32 v39, v98, v38
	v_mov_b32_e32 v9, v144
	v_mov_b32_e32 v8, v145
	s_waitcnt lgkmcnt(0)
	v_add_f32_e32 v38, v38, v39
	ds_bpermute_b32 v39, v99, v38
	s_waitcnt lgkmcnt(0)
	v_add_f32_e32 v40, v38, v39
	ds_bpermute_b32 v41, v100, v40
	v_lshl_add_u64 v[38:39], v[36:37], 0, s[30:31]
	v_add_co_u32_e32 v36, vcc, s41, v36
	s_waitcnt lgkmcnt(0)
	v_add_f32_e32 v40, v40, v41
	v_fmamk_f32 v40, v40, 0x3c000000, v104
	v_mul_f32_e32 v41, 0x4b800000, v40
	v_cmp_gt_f32_e64 s[10:11], s3, v40
	v_addc_co_u32_e32 v37, vcc, 0, v37, vcc
	s_nop 0
	v_cndmask_b32_e64 v40, v40, v41, s[10:11]
	v_rsq_f32_e32 v40, v40
	s_andn2_b64 vcc, exec, s[34:35]
	v_mul_f32_e32 v41, 0x45800000, v40
	v_cndmask_b32_e64 v40, v40, v41, s[10:11]
	v_pk_mul_f32 v[20:21], v[20:21], v[40:41] op_sel_hi:[1,0]
	v_pk_mul_f32 v[22:23], v[22:23], v[40:41] op_sel_hi:[1,0]
	v_pk_mul_f32 v[32:33], v[32:33], v[40:41] op_sel_hi:[1,0]
	v_pk_mul_f32 v[34:35], v[34:35], v[40:41] op_sel_hi:[1,0]
	v_pk_mul_f32 v[24:25], v[24:25], v[40:41] op_sel_hi:[1,0]
	v_pk_mul_f32 v[26:27], v[26:27], v[40:41] op_sel_hi:[1,0]
	v_pk_mul_f32 v[28:29], v[28:29], v[40:41] op_sel_hi:[1,0]
	v_pk_mul_f32 v[30:31], v[30:31], v[40:41] op_sel_hi:[1,0]
	v_pk_mul_f32 v[0:1], v[236:237], v[32:33]
	v_pk_mul_f32 v[4:5], v[240:241], v[20:21]
	v_pk_mul_f32 v[6:7], v[242:243], v[22:23]
	v_pk_mul_f32 v[2:3], v[238:239], v[34:35]
	v_accvgpr_read_b32 v16, a4
	v_accvgpr_read_b32 v17, a5
	v_accvgpr_read_b32 v18, a6
	v_accvgpr_read_b32 v19, a7
	v_accvgpr_read_b32 v12, a0
	v_accvgpr_read_b32 v13, a1
	v_accvgpr_read_b32 v14, a2
	v_accvgpr_read_b32 v15, a3
	v_pk_mul_f32 v[16:17], v[16:17], v[24:25]
	v_pk_mul_f32 v[18:19], v[18:19], v[26:27]
	v_pk_mul_f32 v[12:13], v[12:13], v[28:29]
	v_pk_mul_f32 v[14:15], v[14:15], v[30:31]
	v_pk_mul_f32 v[4:5], v[4:5], v[170:171]
	v_pk_mul_f32 v[6:7], v[6:7], v[172:173]
	v_pk_mul_f32 v[20:21], v[0:1], v[48:49]
	v_pk_mul_f32 v[22:23], v[2:3], v[50:51]
	v_pk_mul_f32 v[16:17], v[16:17], v[174:175]
	v_pk_mul_f32 v[18:19], v[18:19], v[52:53]
	v_pk_mul_f32 v[12:13], v[12:13], v[54:55]
	v_pk_mul_f32 v[14:15], v[14:15], v[176:177]
	v_cvt_pk_bf16_f32 v0, v4, v5
	v_cvt_pk_bf16_f32 v1, v6, v7
	v_cvt_pk_bf16_f32 v2, v20, v21
	v_cvt_pk_bf16_f32 v3, v22, v23
	v_cvt_pk_bf16_f32 v4, v16, v17
	v_cvt_pk_bf16_f32 v5, v18, v19
	v_cvt_pk_bf16_f32 v6, v12, v13
	v_cvt_pk_bf16_f32 v7, v14, v15
	global_store_dwordx4 v[36:37], v[0:3], off offset:2048
	global_store_dwordx4 v[38:39], v[4:7], off offset:16
	v_mov_b32_e32 v15, v130
	v_mov_b32_e32 v14, v125
	v_mov_b32_e32 v13, v126
	v_mov_b32_e32 v12, v127
	s_waitcnt vmcnt(2)
	v_perm_b32 v140, v214, v213, s39
	v_perm_b32 v141, v216, v215, s39
	v_perm_b32 v142, v218, v217, s39
	v_perm_b32 v143, v220, v219, s39
	v_perm_b32 v133, v222, v221, s39
	v_perm_b32 v134, v224, v223, s39
	v_perm_b32 v135, v211, v225, s39
	v_perm_b32 v136, v210, v212, s39
	v_mov_b32_e32 v0, v140
	v_mov_b32_e32 v1, v141
	v_mov_b32_e32 v2, v142
	v_mov_b32_e32 v3, v143
	v_mov_b32_e32 v4, v133
	v_mov_b32_e32 v5, v134
	v_mov_b32_e32 v6, v135
	v_mov_b32_e32 v7, v136
	s_barrier
	s_cbranch_vccz .LBB0_739
